# mLSTM chunk phase dn sum: eight LDS reads per iteration issued together with counted lgkmcnt waits (was one read per lgkmcnt(0))
# speedup vs baseline: 1.0058x; 1.0058x over previous
; #define LAS __attribute__((address_space(3)))
; __device__ __forceinline__ float bf2f(unsigned h) { return __uint_as_float(h << 16); }
; __device__ __forceinline__ void mlstm_a(const bf16* Z, const float* GATES, const float* gbias  , bf16* DC, float* DN, float* SC, LAS unsigned char* L, int wg, int G, int tid) {
;     ...
;         if (w4 < 2) { const int dir = w4; const size_t sidx = (size_t)((b * 4 + h) * 2 + dir) * NSTEP + (dir == 0 ? step0 : step1); float s = 0.f;
; #pragma unroll 8
;             for (int j = 0; j < 64; ++j) s += bf2f(*(LAS const unsigned short*)(kt + dir * 9216 + j * 144 + lane * 2));
;             DN[sidx * 64 + lane] = s; }
.LBB0_596:
	v_add_u32_e32 v3, s26, v50
	ds_read_u16 v4, v3
	ds_read_u16 v5, v3 offset:144
	ds_read_u16 v6, v3 offset:288
	ds_read_u16 v7, v3 offset:432
	ds_read_u16 v8, v3 offset:576
	ds_read_u16 v9, v3 offset:720
	ds_read_u16 v10, v3 offset:864
	ds_read_u16 v11, v3 offset:1008
	s_addk_i32 s26, 0x480
	s_cmpk_eq_i32 s26, 0x2400
	s_waitcnt lgkmcnt(7)
	v_lshlrev_b32_e32 v4, 16, v4
	v_add_f32_e32 v2, v2, v4
	s_waitcnt lgkmcnt(6)
	v_lshlrev_b32_e32 v5, 16, v5
	v_add_f32_e32 v2, v2, v5
	s_waitcnt lgkmcnt(5)
	v_lshlrev_b32_e32 v6, 16, v6
	v_add_f32_e32 v2, v2, v6
	s_waitcnt lgkmcnt(4)
	v_lshlrev_b32_e32 v7, 16, v7
	v_add_f32_e32 v2, v2, v7
	s_waitcnt lgkmcnt(3)
	v_lshlrev_b32_e32 v8, 16, v8
	v_add_f32_e32 v2, v2, v8
	s_waitcnt lgkmcnt(2)
	v_lshlrev_b32_e32 v9, 16, v9
	v_add_f32_e32 v2, v2, v9
	s_waitcnt lgkmcnt(1)
	v_lshlrev_b32_e32 v10, 16, v10
	v_add_f32_e32 v2, v2, v10
	s_waitcnt lgkmcnt(0)
	v_lshlrev_b32_e32 v11, 16, v11
	v_add_f32_e32 v2, v2, v11
	s_cbranch_scc0 .LBB0_596
	v_cndmask_b32_e64 v4, v42, v44, s[6:7]
	v_or_b32_e32 v3, v20, v47
	v_ashrrev_i32_e32 v5, 31, v4
	v_mad_i64_i32 v[4:5], s[26:27], v3, s94, v[4:5]
	v_lshlrev_b64 v[4:5], 8, v[4:5]
	v_lshl_add_u64 v[4:5], v[22:23], 0, v[4:5]
	global_store_dword v[4:5], v2, off
	s_branch .LBB0_566
